# NA fixed-softmax loop: LDS-DMA source addresses from one scalar base per unit + three 32-bit per-lane offsets (replaces 22 per-lane 64-bit VALU adds per iteration)
# baseline (speedup 1.0000x reference)
.LBB0_1262:
	s_or_b64 exec, exec, s[8:9]
	s_lshr_b32 s8, s18, 6
	s_and_b32 s9, s8, 7
	s_lshl_b32 s8, s9, 7
	v_writelane_b32 v254, s8, 56
	s_movk_i32 s16, 0x7c
	v_readlane_b32 s8, v254, 53
	s_and_b32 s15, s8, 63
	v_med3_u32 v0, s15, 4, 60
	v_lshlrev_b32_e32 v1, 16, v0
	v_add_u32_e32 v148, 0xfffc0000, v1
	v_lshl_or_b32 v64, s9, 22, v221
	v_lshlrev_b32_e32 v1, 7, v0
	s_mulk_i32 s9, 0x744
	v_mul_lo_u32 v0, v0, s16
	v_add_u32_e32 v0, s9, v0
	s_mulk_i32 s15, 0x7c
	v_subrev_u32_e32 v0, s15, v0
	v_add_u32_e32 v228, v219, v0
	v_add_u32_e32 v229, v220, v0
	v_med3_u32 v0, s13, 4, 60
	v_writelane_b32 v254, s18, 57
	v_readfirstlane_b32 s9, v0
	s_lshl_b32 s9, s9, 6
	s_add_i32 s18, s9, 0xffffff00
	s_add_u32 s16, vcc_lo, s18
	v_readlane_b32 s8, v254, 37
	v_add_u32_e32 v66, 0xfffffe00, v1
	s_addc_u32 s17, vcc_hi, 0
	v_or_b32_sdwa v0, s14, v145 dst_sel:WORD_1 dst_unused:UNUSED_PAD src0_sel:DWORD src1_sel:DWORD
	v_mov_b32_e32 v1, v149
	v_readlane_b32 s9, v254, 38
	s_lshl_b64 s[16:17], s[16:17], 10
	v_readlane_b32 s13, v254, 36
	v_lshl_add_u64 v[0:1], s[8:9], 0, v[0:1]
	v_readlane_b32 s9, v254, 34
	s_add_u32 s9, s9, s16
	s_addc_u32 s13, s13, s17
	s_lshl_b32 s16, s14, 1
	s_mov_b32 s8, s16
	v_or_b32_e32 v2, s14, v144
	v_writelane_b32 v254, s8, 58
	s_add_u32 s16, s9, s16
	v_lshlrev_b32_e32 v2, 5, v2
	v_mov_b32_e32 v3, v149
	s_addc_u32 s17, s13, 0
	v_lshl_add_u64 v[2:3], v[164:165], 0, v[2:3]
	v_mov_b32_e32 v175, v149
	global_load_dwordx4 v[20:23], v[2:3], off
	global_load_dwordx4 v[16:19], v[2:3], off offset:1024
	v_lshl_add_u64 v[2:3], s[16:17], 0, v[174:175]
	v_mov_b32_e32 v177, v149
	v_mov_b32_e32 v179, v149
	v_lshl_add_u64 v[4:5], v[2:3], 0, v[176:177]
	s_mov_b32 m0, s33
	v_lshl_add_u64 v[2:3], v[2:3], 0, v[178:179]
	s_mov_b64 s[14:15], 0x1000
	s_add_i32 s16, s33, 0x400
	v_lshl_add_u64 v[0:1], vcc, 1, v[0:1]
	v_writelane_b32 v254, s9, 59
	s_mov_b32 s9, s19
	global_load_lds_dwordx4 v[4:5], off
	v_lshl_add_u64 v[6:7], v[2:3], 0, s[14:15]
	s_mov_b32 m0, s16
	s_mov_b64 s[14:15], 0x4000
	s_add_i32 s17, s33, 0x800
	v_writelane_b32 v254, s8, 60
	v_lshl_add_u64 v[0:1], s[18:19], 1, v[0:1]
	global_load_lds_dwordx4 v[6:7], off
	v_lshl_add_u64 v[4:5], v[4:5], 0, s[14:15]
	s_mov_b32 m0, s17
	s_mov_b64 s[14:15], 0x5000
	s_add_i32 s19, s33, 0xc00
	v_writelane_b32 v254, s9, 61
	v_mov_b32_e32 v159, v149
	global_load_lds_dwordx4 v[4:5], off
	v_lshl_add_u64 v[2:3], v[2:3], 0, s[14:15]
	s_mov_b32 m0, s19
	s_add_i32 s8, s33, 0x1000
	v_lshl_add_u64 v[0:1], v[0:1], 0, v[158:159]
	global_load_lds_dwordx4 v[2:3], off
	v_writelane_b32 v254, s8, 62
	s_mov_b32 m0, s8
	s_mov_b64 s[14:15], 0x100000
	s_add_i32 s8, s33, 0x1400
	global_load_lds_dwordx4 v[0:1], off
	v_lshl_add_u64 v[2:3], v[0:1], 0, s[14:15]
	v_writelane_b32 v255, s8, 0
	s_mov_b32 m0, s8
	s_mov_b64 s[14:15], 0x200000
	s_add_i32 s8, s33, 0x1800
	global_load_lds_dwordx4 v[2:3], off
	v_lshl_add_u64 v[2:3], v[0:1], 0, s[14:15]
	s_mov_b32 m0, s8
	s_mov_b64 s[14:15], 0x300000
	s_add_i32 s13, s33, 0x1c00
	global_load_lds_dwordx4 v[2:3], off
	v_lshl_add_u64 v[0:1], v[0:1], 0, s[14:15]
	s_mov_b32 m0, s13
	s_mov_b32 s18, s8
	global_load_lds_dwordx4 v[0:1], off
	s_waitcnt vmcnt(0)
	v_mfma_f32_32x32x16_bf16 v[0:15], v[36:39], v[96:99], 0
	v_readlane_b32 s8, v254, 54
	v_readlane_b32 s9, v254, 55
	v_mov_b32_e32 v67, v149
	s_lshl_b64 s[14:15], s[8:9], 22
	v_readlane_b32 vcc_lo, v254, 56
	s_lshl_b64 s[8:9], s[8:9], 13
	v_mov_b32_e32 v65, v149
	v_mfma_f32_32x32x16_bf16 v[0:15], v[28:31], v[100:103], v[0:15]
	s_or_b32 s14, s14, vcc_lo
	v_lshl_add_u64 v[66:67], v[66:67], 0, s[8:9]
	v_lshl_add_u64 v[64:65], v[66:67], 0, v[64:65]
	v_lshl_add_u64 v[188:189], v[172:173], 0, v[64:65]
	v_mfma_f32_32x32x16_bf16 v[0:15], v[32:35], v[104:107], v[0:15]
	v_mfma_f32_32x32x16_bf16 v[0:15], v[24:27], v[108:111], v[0:15]
	s_nop 11
	v_exp_f32_e32 v68, v0
	v_exp_f32_e32 v72, v1
	v_exp_f32_e32 v70, v2
	v_exp_f32_e32 v76, v3
	v_exp_f32_e32 v74, v4
	v_exp_f32_e32 v80, v5
	v_exp_f32_e32 v78, v6
	v_exp_f32_e32 v82, v7
	v_mfma_f32_32x32x16_bf16 v[0:15], v[36:39], v[112:115], 0
	v_mfma_f32_32x32x16_bf16 v[0:15], v[28:31], v[116:119], v[0:15]
	v_mfma_f32_32x32x16_bf16 v[0:15], v[32:35], v[120:123], v[0:15]
	v_mfma_f32_32x32x16_bf16 v[0:15], v[24:27], v[124:127], v[0:15]
	s_nop 11
	v_exp_f32_e32 v69, v0
	v_exp_f32_e32 v73, v1
	v_exp_f32_e32 v71, v2
	v_exp_f32_e32 v77, v3
	v_exp_f32_e32 v75, v4
	v_exp_f32_e32 v81, v5
	v_exp_f32_e32 v79, v6
	v_exp_f32_e32 v83, v7
	v_pk_add_f32 v[0:1], v[68:69], 0 op_sel_hi:[1,0]
	v_pk_add_f32 v[2:3], v[72:73], 0 op_sel_hi:[1,0]
	v_pk_add_f32 v[0:1], v[70:71], v[0:1]
	v_pk_add_f32 v[2:3], v[76:77], v[2:3]
	v_pk_add_f32 v[0:1], v[74:75], v[0:1]
	v_pk_add_f32 v[2:3], v[80:81], v[2:3]
	v_pk_add_f32 v[4:5], v[78:79], v[0:1]
	v_pk_add_f32 v[6:7], v[82:83], v[2:3]
	v_cvt_pk_bf16_f32 v0, v68, v72
	v_cvt_pk_bf16_f32 v1, v70, v76
	v_cvt_pk_bf16_f32 v2, v74, v80
	v_cvt_pk_bf16_f32 v3, v78, v82
	v_cvt_pk_bf16_f32 v24, v69, v73
	v_cvt_pk_bf16_f32 v25, v71, v77
	v_cvt_pk_bf16_f32 v26, v75, v81
	v_cvt_pk_bf16_f32 v27, v79, v83
	v_mfma_f32_32x32x16_bf16 v[32:47], v[20:23], v[0:3], 0
	v_add_f32_e64 v190, v6, v4
	v_add_f32_e64 v191, v7, v5
	v_lshl_add_u64 v[68:69], s[14:15], 0, v[148:149]
	v_lshl_add_u64 v[184:185], v[168:169], 0, v[68:69]
	v_lshl_add_u64 v[186:187], v[170:171], 0, v[68:69]
	v_mfma_f32_32x32x16_bf16 v[48:63], v[16:19], v[0:3], 0
	v_mfma_f32_32x32x16_bf16 v[0:15], v[20:23], v[24:27], 0
	v_mfma_f32_32x32x16_bf16 v[16:31], v[16:19], v[24:27], 0
	v_readfirstlane_b32 s32, v184
	v_readfirstlane_b32 s100, v185
	s_nop 1
	s_sub_u32 s32, s32, 0x80
	s_subb_u32 s100, s100, 0
	v_subrev_u32_e32 v231, s32, v184
	v_subrev_u32_e32 v232, s32, v186
	v_subrev_u32_e32 v233, s32, v188
	v_add_u32_e32 v233, 0x4000000, v233
	s_nop 0
	s_add_u32 s32, s32, s10
	s_addc_u32 s100, s100, s11
	s_branch .LBB0_1264
.LBB0_1263:
	v_add_f32_e32 v64, 0, v148
	v_add_f32_e32 v65, 0, v177
	v_add_f32_e32 v64, v64, v179
	v_add_f32_e32 v65, v65, v202
	v_add_f32_e32 v64, v64, v203
	v_add_f32_e32 v65, v65, v204
	v_add_f32_e32 v148, v64, v205
	v_add_f32_e32 v64, v65, v230
	v_mov_b32_e32 v65, v149
	v_pk_add_f32 v[66:67], v[148:149], v[74:75]
	v_pk_add_f32 v[64:65], v[64:65], v[72:73]
	v_pk_add_f32 v[66:67], v[66:67], v[68:69]
	v_pk_add_f32 v[64:65], v[64:65], v[70:71]
	v_pk_add_f32 v[66:67], v[66:67], v[78:79]
	v_pk_add_f32 v[64:65], v[64:65], v[198:199]
	v_pk_add_f32 v[66:67], v[66:67], v[76:77]
	v_pk_add_f32 v[64:65], v[64:65], v[200:201]
	v_readlane_b32 s14, v254, 41
	v_pk_add_f32 v[64:65], v[66:67], v[64:65]
	v_readlane_b32 s15, v254, 42
	v_pk_add_f32 v[190:191], v[190:191], v[64:65]
	v_mfma_f32_32x32x16_bf16 v[64:79], v[140:143], v[96:99], 0
	s_add_i32 s12, s12, 2
	v_add_u32_e32 v233, 0x80, v233
	v_add_u32_e32 v228, 0x7c, v228
	v_add_u32_e32 v229, 0x7c, v229
	s_andn2_b64 vcc, exec, s[8:9]
	s_waitcnt lgkmcnt(0)
	v_mfma_f32_32x32x16_bf16 v[64:79], v[136:139], v[100:103], v[64:79]
	v_mfma_f32_32x32x16_bf16 v[64:79], v[128:131], v[104:107], v[64:79]
	v_mfma_f32_32x32x16_bf16 v[64:79], v[132:135], v[108:111], v[64:79]
	s_nop 11
	v_add_u32_e32 v71, 0x20330, v175
	ds_read2_b32 v[72:73], v71 offset1:1
	s_waitcnt lgkmcnt(0)
	v_add_f32_e32 v64, v64, v72
	v_cndmask_b32_e64 v71, v216, v64, s[60:61]
	v_add_f32_e32 v64, v65, v73
	v_cndmask_b32_e64 v72, v216, v64, s[62:63]
	v_add_u32_e32 v64, 0x20338, v175
	ds_read2_b32 v[64:65], v64 offset1:1
	v_exp_f32_e32 v194, v71
	v_exp_f32_e32 v192, v72
	s_waitcnt lgkmcnt(0)
	v_add_f32_e32 v64, v66, v64
	v_cndmask_b32_e64 v66, v216, v64, s[64:65]
	v_add_f32_e32 v64, v67, v65
	v_cndmask_b32_e64 v67, v216, v64, s[66:67]
	v_add_u32_e32 v64, 0x20340, v175
	ds_read2_b32 v[64:65], v64 offset1:1
	v_exp_f32_e32 v198, v66
	v_exp_f32_e32 v196, v67
	s_waitcnt lgkmcnt(0)
	v_add_f32_e32 v64, v68, v64
	v_add_u32_e32 v68, 0x20348, v175
	ds_read_b32 v68, v68
	v_add_f32_e32 v65, v69, v65
	v_cndmask_b32_e64 v64, v216, v64, s[68:69]
	v_cndmask_b32_e64 v65, v216, v65, s[70:71]
	v_exp_f32_e32 v202, v64
	s_waitcnt lgkmcnt(0)
	v_add_f32_e32 v68, v70, v68
	v_cndmask_b32_e64 v68, v216, v68, s[72:73]
	v_exp_f32_e32 v200, v65
	v_exp_f32_e32 v204, v68
	v_mfma_f32_32x32x16_bf16 v[64:79], v[140:143], v[112:115], 0
	v_mfma_f32_32x32x16_bf16 v[64:79], v[136:139], v[116:119], v[64:79]
	v_mfma_f32_32x32x16_bf16 v[64:79], v[128:131], v[120:123], v[64:79]
	v_add_u32_e32 v128, 0x20330, v159
	ds_read2_b32 v[128:129], v128 offset1:1
	v_mfma_f32_32x32x16_bf16 v[64:79], v[132:135], v[124:127], v[64:79]
	s_waitcnt lgkmcnt(0)
	s_nop 10
	v_add_f32_e32 v64, v64, v128
	v_cndmask_b32_e64 v128, v216, v64, s[14:15]
	v_add_f32_e32 v64, v65, v129
	v_cndmask_b32_e64 v129, v216, v64, s[74:75]
	v_add_u32_e32 v64, 0x20338, v159
	ds_read2_b32 v[64:65], v64 offset1:1
	v_add_u32_e32 v231, 0x10000, v231
	v_add_u32_e32 v232, 0x10000, v232
	s_waitcnt lgkmcnt(0)
	v_add_f32_e32 v64, v66, v64
	v_cndmask_b32_e64 v66, v216, v64, s[76:77]
	v_add_f32_e32 v64, v67, v65
	v_cndmask_b32_e64 v67, v216, v64, s[78:79]
	v_add_u32_e32 v64, 0x20340, v159
	ds_read2_b32 v[64:65], v64 offset1:1
	v_exp_f32_e32 v130, v66
	v_exp_f32_e32 v131, v67
	s_waitcnt lgkmcnt(0)
	v_add_f32_e32 v64, v68, v64
	v_cndmask_b32_e64 v68, v216, v64, s[80:81]
	v_add_f32_e32 v64, v69, v65
	v_cndmask_b32_e64 v69, v216, v64, s[82:83]
	v_add_u32_e32 v64, 0x20348, v159
	ds_read2_b32 v[64:65], v64 offset1:1
	s_waitcnt lgkmcnt(0)
	v_add_f32_e32 v64, v70, v64
	v_cndmask_b32_e64 v70, v216, v64, s[84:85]
	v_add_f32_e32 v64, v71, v65
	v_cndmask_b32_e64 v71, v216, v64, s[86:87]
	v_add_u32_e32 v64, 0x20370, v159
	ds_read2_b32 v[64:65], v64 offset1:1
	v_exp_f32_e32 v132, v70
	v_exp_f32_e32 v133, v71
	v_mov_b32_e32 v70, v149
	s_waitcnt lgkmcnt(0)
	v_add_f32_e32 v64, v72, v64
	v_cndmask_b32_e64 v72, v216, v64, s[88:89]
	v_add_f32_e32 v64, v73, v65
	v_cndmask_b32_e64 v73, v216, v64, s[90:91]
	v_add_u32_e32 v64, 0x20378, v159
	ds_read2_b32 v[64:65], v64 offset1:1
	v_exp_f32_e32 v72, v72
	v_exp_f32_e32 v195, v73
	s_waitcnt lgkmcnt(0)
	v_add_f32_e32 v64, v74, v64
	v_cndmask_b32_e64 v74, v216, v64, s[92:93]
	v_add_f32_e32 v64, v75, v65
	v_cndmask_b32_e64 v75, v216, v64, s[94:95]
	v_add_u32_e32 v64, 0x20380, v159
	ds_read2_b32 v[64:65], v64 offset1:1
	v_exp_f32_e32 v193, v74
	v_exp_f32_e32 v199, v75
	s_waitcnt lgkmcnt(0)
	v_add_f32_e32 v64, v76, v64
	v_cndmask_b32_e64 v76, v216, v64, s[96:97]
	v_add_f32_e32 v64, v77, v65
	v_cndmask_b32_e64 v77, v216, v64, s[2:3]
	v_add_u32_e32 v64, 0x20388, v159
	ds_read2_b32 v[64:65], v64 offset1:1
	v_exp_f32_e32 v197, v76
	v_exp_f32_e32 v203, v77
	s_waitcnt lgkmcnt(0)
	v_add_f32_e32 v64, v78, v64
	v_exp_f32_e32 v78, v128
	v_add_f32_e32 v65, v79, v65
	v_exp_f32_e32 v79, v129
	v_cndmask_b32_e64 v64, v216, v64, s[4:5]
	v_add_f32_e32 v128, 0, v78
	v_add_f32_e32 v66, v128, v130
	v_add_f32_e32 v129, 0, v79
	v_exp_f32_e32 v128, v68
	v_add_f32_e32 v67, v129, v131
	v_exp_f32_e32 v129, v69
	v_cndmask_b32_e64 v65, v216, v65, s[0:1]
	v_add_f32_e32 v66, v66, v128
	v_add_f32_e32 v66, v66, v132
	v_add_f32_e32 v67, v67, v129
	v_add_f32_e32 v69, v67, v133
	v_add_f32_e32 v71, v66, v72
	v_exp_f32_e32 v201, v64
	v_exp_f32_e32 v205, v65
	v_cvt_pk_bf16_f32 v64, v194, v192
	v_cvt_pk_bf16_f32 v65, v198, v196
	v_cvt_pk_bf16_f32 v66, v202, v200
	v_cvt_pk_bf16_f32 v67, v204, 0
	v_mov_b32_e32 v68, v149
	v_pk_add_f32 v[68:69], v[68:69], v[194:195]
	v_mfma_f32_32x32x16_bf16 v[32:47], v[92:95], v[64:67], v[32:47]
	v_add_f32_e64 v70, v70, v192
	v_add_f32_e64 v71, v71, v193
	v_add_f32_e64 v68, v68, v198
	v_add_f32_e64 v69, v69, v199
	v_add_f32_e64 v70, v70, v196
	v_add_f32_e64 v71, v71, v197
	v_pk_add_f32 v[68:69], v[68:69], v[202:203]
	v_pk_add_f32 v[70:71], v[70:71], v[200:201]
	v_pk_add_f32 v[68:69], v[68:69], v[204:205]
	v_mfma_f32_32x32x16_bf16 v[48:63], v[88:91], v[64:67], v[48:63]
	v_cvt_pk_bf16_f32 v64, v78, v79
	v_cvt_pk_bf16_f32 v65, v130, v131
	v_cvt_pk_bf16_f32 v66, v128, v129
	v_cvt_pk_bf16_f32 v67, v132, v133
	v_add_f32_e64 v68, v70, v68
	v_add_f32_e64 v69, v71, v69
	v_pk_add_f32 v[190:191], v[190:191], v[68:69]
	v_mfma_f32_32x32x16_bf16 v[0:15], v[92:95], v[64:67], v[0:15]
	v_mfma_f32_32x32x16_bf16 v[16:31], v[88:91], v[64:67], v[16:31]
	v_cvt_pk_bf16_f32 v64, v72, v195
	v_cvt_pk_bf16_f32 v65, v193, v199
	v_cvt_pk_bf16_f32 v66, v197, v203
	v_cvt_pk_bf16_f32 v67, v201, v205
	s_nop 1
	v_mfma_f32_32x32x16_bf16 v[0:15], v[84:87], v[64:67], v[0:15]
	v_mfma_f32_32x32x16_bf16 v[16:31], v[80:83], v[64:67], v[16:31]
	s_cbranch_vccz .LBB0_1253
.LBB0_1264:
	s_waitcnt vmcnt(0)
	ds_read_b128 v[80:83], v222
	ds_read_b128 v[136:139], v223
	ds_read_b128 v[132:135], v224
	ds_read_b128 v[128:131], v225
	ds_read_b128 v[84:87], v226 offset:4096
	s_add_i32 m0, s33, 0x2000
	s_add_u32 s98, s32, 0x17608000
	s_addc_u32 s99, s100, 0
	global_load_lds_dwordx4 v231, s[98:99]
	s_add_i32 m0, s33, 0x2400
	s_add_u32 s98, s32, 0x17609000
	s_addc_u32 s99, s100, 0
	global_load_lds_dwordx4 v232, s[98:99]
	s_add_i32 m0, s33, 0x2800
	s_add_u32 s98, s32, 0x1760c000
	s_addc_u32 s99, s100, 0
	global_load_lds_dwordx4 v231, s[98:99]
	s_add_i32 m0, s33, 0x2c00
	s_add_u32 s98, s32, 0x1760d000
	s_addc_u32 s99, s100, 0
	global_load_lds_dwordx4 v232, s[98:99]
	s_add_i32 m0, s33, 0x3000
	s_add_u32 s98, s32, 0x15600040
	s_addc_u32 s99, s100, 0
	global_load_lds_dwordx4 v233, s[98:99]
	s_add_i32 m0, s33, 0x3400
	s_add_u32 s98, s32, 0x15700040
	s_addc_u32 s99, s100, 0
	global_load_lds_dwordx4 v233, s[98:99]
	s_add_i32 m0, s33, 0x3800
	s_add_u32 s98, s32, 0x15800040
	s_addc_u32 s99, s100, 0
	global_load_lds_dwordx4 v233, s[98:99]
	s_add_i32 m0, s33, 0x3c00
	s_add_u32 s98, s32, 0x15900040
	s_addc_u32 s99, s100, 0
	global_load_lds_dwordx4 v233, s[98:99]
	s_waitcnt lgkmcnt(0)
	v_mfma_f32_32x32x16_bf16 v[64:79], v[80:83], v[96:99], 0
	v_mfma_f32_32x32x16_bf16 v[64:79], v[136:139], v[100:103], v[64:79]
	v_mfma_f32_32x32x16_bf16 v[64:79], v[132:135], v[104:107], v[64:79]
	v_mfma_f32_32x32x16_bf16 v[64:79], v[128:131], v[108:111], v[64:79]
	v_add_u32_e32 v175, v229, v163
	v_add_u32_e32 v88, 0x202b0, v175
	ds_read2_b32 v[88:89], v88 offset1:1
	v_add_u32_e32 v90, 0x202b8, v175
	ds_read2_b32 v[90:91], v90 offset1:1
	v_readlane_b32 s8, v254, 45
	v_readlane_b32 s9, v254, 46
	s_waitcnt lgkmcnt(0)
	s_nop 4
	v_add_f32_e32 v64, v64, v88
	v_add_u32_e32 v159, v228, v163
	v_cndmask_b32_e64 v88, v216, v64, s[8:9]
	v_readlane_b32 s8, v254, 47
	v_add_f32_e32 v64, v65, v89
	v_readlane_b32 s9, v254, 48
	v_exp_f32_e32 v148, v88
	s_cmp_gt_u32 s12, 13
	v_cndmask_b32_e64 v89, v216, v64, s[8:9]
	v_readlane_b32 s8, v254, 49
	v_add_f32_e32 v64, v66, v90
	v_readlane_b32 s9, v254, 50
	v_add_f32_e32 v66, v67, v91
	v_exp_f32_e32 v177, v89
	v_cndmask_b32_e64 v90, v216, v64, s[8:9]
	v_readlane_b32 s8, v254, 51
	v_readlane_b32 s9, v254, 52
	v_add_u32_e32 v64, 0x202c0, v175
	ds_read2_b32 v[64:65], v64 offset1:1
	v_cndmask_b32_e64 v91, v216, v66, s[8:9]
	v_add_u32_e32 v66, 0x202c8, v175
	ds_read2_b32 v[66:67], v66 offset1:1
	v_exp_f32_e32 v179, v90
	s_waitcnt lgkmcnt(0)
	v_add_f32_e32 v64, v68, v64
	v_add_f32_e32 v65, v69, v65
	v_cndmask_b32_e64 v64, v216, v64, s[20:21]
	v_add_f32_e32 v66, v70, v66
	v_add_f32_e32 v67, v71, v67
	v_cndmask_b32_e64 v65, v216, v65, s[22:23]
	v_cndmask_b32_e64 v66, v216, v66, s[24:25]
	v_cndmask_b32_e64 v67, v216, v67, s[26:27]
	v_exp_f32_e32 v202, v91
	v_exp_f32_e32 v203, v64
	v_exp_f32_e32 v204, v65
	v_exp_f32_e32 v205, v66
	v_exp_f32_e32 v230, v67
	v_cvt_pk_bf16_f32 v140, v148, v177
	v_cvt_pk_bf16_f32 v141, v179, v202
	v_cvt_pk_bf16_f32 v142, v203, v204
	v_cvt_pk_bf16_f32 v143, v205, v230
	v_add_u32_e32 v68, 0x202f0, v175
	ds_read2_b32 v[68:69], v68 offset1:1
	v_mfma_f32_32x32x16_bf16 v[32:47], v[84:87], v[140:143], v[32:47]
	v_add_u32_e32 v70, 0x202f8, v175
	ds_read_b128 v[154:157], v226 offset:6144
	ds_read_b128 v[64:67], v227 offset:4096
	ds_read2_b32 v[70:71], v70 offset1:1
	s_waitcnt lgkmcnt(0)
	v_add_f32_e32 v68, v72, v68
	v_cndmask_b32_e64 v72, v216, v68, s[6:7]
	v_add_f32_e32 v68, v73, v69
	v_cndmask_b32_e64 v73, v216, v68, s[30:31]
	v_mfma_f32_32x32x16_bf16 v[80:95], v[80:83], v[112:115], 0
	v_add_f32_e32 v68, v74, v70
	v_cndmask_b32_e64 v150, v216, v68, s[34:35]
	v_add_u32_e32 v68, 0x20300, v175
	ds_read2_b32 v[68:69], v68 offset1:1
	v_add_f32_e32 v70, v75, v71
	v_cndmask_b32_e64 v75, v216, v70, s[36:37]
	v_add_u32_e32 v70, 0x20308, v175
	v_mfma_f32_32x32x16_bf16 v[80:95], v[136:139], v[116:119], v[80:95]
	s_waitcnt lgkmcnt(0)
	v_add_f32_e32 v68, v76, v68
	v_cndmask_b32_e64 v76, v216, v68, s[38:39]
	v_add_f32_e32 v68, v77, v69
	v_cndmask_b32_e64 v69, v216, v68, s[40:41]
	v_exp_f32_e32 v198, v69
	v_add_u32_e32 v69, 0x202f0, v159
	ds_read2_b32 v[70:71], v70 offset1:1
	v_mfma_f32_32x32x16_bf16 v[80:95], v[132:135], v[120:123], v[80:95]
	v_exp_f32_e32 v74, v72
	v_exp_f32_e32 v72, v73
	v_readlane_b32 s8, v254, 43
	s_waitcnt lgkmcnt(0)
	v_add_f32_e32 v68, v78, v70
	v_cndmask_b32_e64 v77, v216, v68, s[42:43]
	v_add_f32_e32 v68, v79, v71
	v_cndmask_b32_e64 v71, v216, v68, s[44:45]
	v_mfma_f32_32x32x16_bf16 v[80:95], v[128:131], v[124:127], v[80:95]
	v_exp_f32_e32 v78, v76
	v_exp_f32_e32 v76, v77
	v_exp_f32_e32 v200, v71
	v_readlane_b32 s9, v254, 44
	v_exp_f32_e32 v68, v150
	s_nop 6
	ds_read2_b32 v[80:81], v69 offset1:1
	v_add_u32_e32 v69, 0x202f8, v159
	ds_read2_b32 v[82:83], v69 offset1:1
	v_exp_f32_e32 v70, v75
	v_mfma_f32_32x32x16_bf16 v[48:63], v[154:157], v[140:143], v[48:63]
	s_waitcnt lgkmcnt(0)
	v_add_f32_e32 v69, v88, v80
	v_add_f32_e32 v71, v89, v81
	v_add_f32_e32 v73, v90, v82
	v_cndmask_b32_e64 v77, v216, v73, s[48:49]
	v_add_u32_e32 v73, 0x20300, v159
	ds_read2_b32 v[80:81], v73 offset1:1
	v_add_f32_e32 v73, v91, v83
	v_cndmask_b32_e64 v79, v216, v73, s[50:51]
	v_add_u32_e32 v73, 0x20308, v159
	ds_read2_b32 v[82:83], v73 offset1:1
	s_waitcnt lgkmcnt(0)
	v_add_f32_e32 v73, v92, v80
	v_cndmask_b32_e64 v80, v216, v73, s[52:53]
	v_add_f32_e32 v73, v93, v81
	v_cndmask_b32_e64 v84, v216, v73, s[54:55]
	v_add_f32_e32 v73, v94, v82
	v_cndmask_b32_e64 v85, v216, v73, s[56:57]
	v_add_f32_e32 v73, v95, v83
	v_cndmask_b32_e64 v69, v216, v69, s[8:9]
	v_cndmask_b32_e64 v71, v216, v71, s[46:47]
	v_cndmask_b32_e64 v86, v216, v73, s[58:59]
	v_exp_f32_e32 v75, v69
	v_exp_f32_e32 v73, v71
	v_exp_f32_e32 v69, v77
	v_exp_f32_e32 v71, v79
	v_exp_f32_e32 v79, v80
	v_exp_f32_e32 v199, v84
	v_exp_f32_e32 v77, v85
	v_exp_f32_e32 v201, v86
	v_cvt_pk_bf16_f32 v80, v74, v72
	v_cvt_pk_bf16_f32 v81, v68, v70
	v_cvt_pk_bf16_f32 v82, v78, v198
	v_cvt_pk_bf16_f32 v83, v76, v200
	v_cvt_pk_bf16_f32 v154, v75, v73
	v_cvt_pk_bf16_f32 v155, v69, v71
	v_cvt_pk_bf16_f32 v156, v79, v199
	v_cvt_pk_bf16_f32 v157, v77, v201
	v_mfma_f32_32x32x16_bf16 v[32:47], v[64:67], v[80:83], v[32:47]
	s_cselect_b64 s[8:9], -1, 0
	s_and_b64 vcc, exec, s[8:9]
	v_mfma_f32_32x32x16_bf16 v[0:15], v[64:67], v[154:157], v[0:15]
	ds_read_b128 v[64:67], v227 offset:6144
	s_waitcnt vmcnt(0)
	ds_read_b128 v[140:143], v222 offset:8192
	s_waitcnt lgkmcnt(0)
	v_mfma_f32_32x32x16_bf16 v[48:63], v[64:67], v[80:83], v[48:63]
	ds_read_b128 v[136:139], v223 offset:8192
	ds_read_b128 v[128:131], v224 offset:8192
	ds_read_b128 v[132:135], v225 offset:8192
	ds_read_b128 v[92:95], v226 offset:12288
	ds_read_b128 v[88:91], v226 offset:14336
	ds_read_b128 v[84:87], v227 offset:12288
	ds_read_b128 v[80:83], v227 offset:14336
	v_mfma_f32_32x32x16_bf16 v[16:31], v[64:67], v[154:157], v[16:31]
	s_cbranch_vccnz .LBB0_1263
	s_mov_b32 m0, s33
	s_add_u32 s98, s32, 0x17610000
	s_addc_u32 s99, s100, 0
	global_load_lds_dwordx4 v231, s[98:99]
	s_add_i32 m0, s33, 0x400
	s_add_u32 s98, s32, 0x17611000
	s_addc_u32 s99, s100, 0
	global_load_lds_dwordx4 v232, s[98:99]
	s_add_i32 m0, s33, 0x800
	s_add_u32 s98, s32, 0x17614000
	s_addc_u32 s99, s100, 0
	global_load_lds_dwordx4 v231, s[98:99]
	s_add_i32 m0, s33, 0xc00
	s_add_u32 s98, s32, 0x17615000
	s_addc_u32 s99, s100, 0
	global_load_lds_dwordx4 v232, s[98:99]
	s_add_i32 m0, s33, 0x1000
	s_add_u32 s98, s32, 0x15600080
	s_addc_u32 s99, s100, 0
	global_load_lds_dwordx4 v233, s[98:99]
	s_add_i32 m0, s33, 0x1400
	s_add_u32 s98, s32, 0x15700080
	s_addc_u32 s99, s100, 0
	global_load_lds_dwordx4 v233, s[98:99]
	s_add_i32 m0, s33, 0x1800
	s_add_u32 s98, s32, 0x15800080
	s_addc_u32 s99, s100, 0
	global_load_lds_dwordx4 v233, s[98:99]
	s_add_i32 m0, s33, 0x1c00
	s_add_u32 s98, s32, 0x15900080
	s_addc_u32 s99, s100, 0
	global_load_lds_dwordx4 v233, s[98:99]
	s_branch .LBB0_1263
